# nt hint on the 16 read-once f32 x loads of the P0 x-to-bf16 conversion loop (on top of static prio raise)
# speedup vs baseline: 1.0103x; 1.0103x over previous
.LBB0_852:
	v_lshl_add_u64 v[6:7], s[24:25], 0, v[138:139]
	global_load_dwordx4 v[70:73], v[6:7], off nt
	global_load_dwordx4 v[74:77], v[6:7], off offset:1024 nt
	global_load_dwordx4 v[78:81], v[6:7], off offset:2048 nt
	v_lshl_add_u64 v[8:9], s[34:35], 0, v[138:139]
	global_load_dwordx4 v[82:85], v[6:7], off offset:3072 nt
	global_load_dwordx4 v[50:53], v[8:9], off nt
	global_load_dwordx4 v[46:49], v[8:9], off offset:1024 nt
	global_load_dwordx4 v[42:45], v[8:9], off offset:2048 nt
	global_load_dwordx4 v[34:37], v[8:9], off offset:3072 nt
	s_waitcnt lgkmcnt(0)
	v_and_b32_e32 v1, 64, v228
	v_xor_b32_e32 v10, 1, v228
	v_add_u32_e32 v1, 64, v1
	v_xor_b32_e32 v11, 2, v228
	v_cmp_lt_i32_e64 s[36:37], v10, v1
	s_mul_i32 s3, s26, 24
	v_xor_b32_e32 v12, 4, v228
	v_cndmask_b32_e64 v8, v228, v10, s[36:37]
	v_cmp_lt_i32_e64 s[36:37], v11, v1
	s_add_i32 s42, s9, s2
	v_xor_b32_e32 v13, 8, v228
	s_add_i32 s40, s3, s2
	v_cndmask_b32_e64 v9, v228, v11, s[36:37]
	v_cmp_lt_i32_e64 s[36:37], v12, v1
	v_xor_b32_e32 v14, 16, v228
	s_ashr_i32 s43, s42, 31
	s_ashr_i32 s41, s40, 31
	v_cndmask_b32_e64 v10, v228, v12, s[36:37]
	v_cmp_lt_i32_e64 s[36:37], v13, v1
	v_xor_b32_e32 v15, 32, v228
	s_lshl_b64 s[4:5], s[42:43], 12
	v_cndmask_b32_e64 v11, v228, v13, s[36:37]
	v_cmp_lt_i32_e64 s[36:37], v14, v1
	s_lshl_b64 s[6:7], s[40:41], 12
	v_lshl_add_u64 v[6:7], v[58:59], 0, s[4:5]
	v_cndmask_b32_e64 v12, v228, v14, s[36:37]
	v_cmp_lt_i32_e64 s[36:37], v15, v1
	v_lshlrev_b32_e32 v68, 2, v8
	v_lshlrev_b32_e32 v67, 2, v9
	v_lshl_add_u64 v[8:9], v[58:59], 0, s[6:7]
	v_cndmask_b32_e64 v1, v228, v15, s[36:37]
	v_lshlrev_b32_e32 v66, 2, v10
	v_lshlrev_b32_e32 v65, 2, v11
	v_lshlrev_b32_e32 v64, 2, v12
	global_load_dwordx4 v[38:41], v[6:7], off nt
	global_load_dwordx4 v[30:33], v[6:7], off offset:1024 nt
	global_load_dwordx4 v[26:29], v[6:7], off offset:2048 nt
	global_load_dwordx4 v[22:25], v[6:7], off offset:3072 nt
	global_load_dwordx4 v[18:21], v[8:9], off nt
	global_load_dwordx4 v[14:17], v[8:9], off offset:1024 nt
	global_load_dwordx4 v[10:13], v[8:9], off offset:2048 nt
	s_nop 0
	global_load_dwordx4 v[6:9], v[8:9], off offset:3072 nt
	v_lshl_add_u64 v[86:87], s[30:31], 0, v[54:55]
	v_lshlrev_b32_e32 v1, 2, v1
	s_waitcnt vmcnt(0)
	v_mul_f32_e32 v69, v71, v71
	v_mul_f32_e32 v88, v73, v73
	v_fmac_f32_e32 v69, v70, v70
	v_fmac_f32_e32 v88, v72, v72
	v_cvt_pk_bf16_f32 v70, v70, v70
	v_cvt_pk_bf16_f32 v72, v72, v72
	v_cvt_pk_bf16_f32 v71, v71, v71
	v_cvt_pk_bf16_f32 v73, v73, v73
	v_mul_f32_e32 v94, v77, v77
	v_bfi_b32 v70, s33, v71, v70
	v_bfi_b32 v71, s33, v73, v72
	v_mul_f32_e32 v93, v75, v75
	v_fmac_f32_e32 v94, v76, v76
	v_cvt_pk_bf16_f32 v76, v76, v76
	global_store_dwordx2 v[86:87], v[70:71], off
	v_fmac_f32_e32 v93, v74, v74
	v_cvt_pk_bf16_f32 v74, v74, v74
	v_cvt_pk_bf16_f32 v71, v77, v77
	v_cvt_pk_bf16_f32 v75, v75, v75
	v_bfi_b32 v73, s33, v71, v76
	v_mul_f32_e32 v70, v79, v79
	v_mul_f32_e32 v71, v81, v81
	v_bfi_b32 v72, s33, v75, v74
	v_fmac_f32_e32 v70, v78, v78
	v_fmac_f32_e32 v71, v80, v80
	v_add_f32_e32 v69, v69, v88
	v_add_f32_e32 v88, v93, v94
	global_store_dwordx2 v[86:87], v[72:73], off offset:512
	v_add_f32_e32 v70, v70, v71
	v_mul_f32_e32 v71, v83, v83
	v_mul_f32_e32 v72, v85, v85
	v_add_f32_e32 v69, v69, v88
	v_fmac_f32_e32 v71, v82, v82
	v_fmac_f32_e32 v72, v84, v84
	v_add_f32_e32 v69, v69, v70
	v_add_f32_e32 v71, v71, v72
	v_add_f32_e32 v69, v69, v71
	ds_bpermute_b32 v71, v68, v69
	v_cvt_pk_bf16_f32 v70, v78, v79
	s_waitcnt lgkmcnt(0)
	v_add_f32_e32 v69, v69, v71
	ds_bpermute_b32 v71, v67, v69
	s_waitcnt lgkmcnt(0)
	v_add_f32_e32 v69, v69, v71
	ds_bpermute_b32 v74, v66, v69
	v_cvt_pk_bf16_f32 v71, v80, v81
	s_waitcnt lgkmcnt(0)
	v_add_f32_e32 v69, v69, v74
	global_store_dwordx2 v[86:87], v[70:71], off offset:1024
	ds_bpermute_b32 v71, v65, v69
	v_cvt_pk_bf16_f32 v72, v82, v83
	s_waitcnt lgkmcnt(0)
	v_add_f32_e32 v69, v69, v71
	ds_bpermute_b32 v71, v64, v69
	s_waitcnt lgkmcnt(0)
	v_add_f32_e32 v69, v69, v71
	ds_bpermute_b32 v70, v1, v69
	v_cvt_pk_bf16_f32 v73, v84, v85
	global_store_dwordx2 v[86:87], v[72:73], off offset:1536
	s_and_saveexec_b64 s[36:37], vcc
	s_cbranch_execz .LBB0_854
	s_waitcnt lgkmcnt(0)
	v_add_f32_e32 v69, v69, v70
	v_cndmask_b32_e64 v69, 0, v69, s[0:1]
	v_lshl_add_u64 v[70:71], v[62:63], 0, s[38:39]
	global_store_dword v[70:71], v69, off
